# attention loops: removed redundant s_nop pads (MFMA->VALU distance already covered), max-canonicalisation, dead m0 save/restore, merged MLA PV lgkmcnt waits, de-chained packed row-sum adds
# speedup vs baseline: 1.0147x; 1.0147x over previous
; #define ATT_DMA_K(tt, kslot) do { \
;         glds16(ksrc + (size_t)(tt) * 64 * pitchK, (unsigned)__builtin_amdgcn_readfirstlane(lds0 + (kslot) * KB + wid * 1024)); \
;         if (MLA) glds16(rsrc + (size_t)(tt) * 64 * 32, (unsigned)__builtin_amdgcn_readfirstlane(lds0 + KROFF + (kslot) * KRB + (wid & 3) * 1024)); } while (0)
; #define ATT_DMA_V(tt, vslot) do { \
;         _Pragma("unroll") for (int j = 0; j < NVC; ++j) glds16(vsrc[j] + (size_t)(tt) * (512 * 64), (unsigned)__builtin_amdgcn_readfirstlane(lds0 + VOFF + (vslot) * VB + (wid + 8 * j) * 1024)); } while (0)
; template <int DQK, int DV, bool MLA>
; __device__ __forceinline__ void attn_pass(LAS unsigned char* lds, const bf16_t* Qrow, const bf16_t* K0, int pitchK, const bf16_t* KrB, const bf16_t* Vt0, int NT, int q0w,
;                                           f32x16 (&o)[DV / 32], float& l_out, int tid) {
;     ...
;     for (int t = 0; t < NT; ++t) {
;         const bool far = t + 3 < NT;
;         if (far) ATT_DMA_K(t + 3, (t + 3) & 3);
;         if (t + 2 < NT) ATT_DMA_V(t + 2, (t + 2) & 3);
.LBB0_59:
	s_add_i32 s7, s57, 7
	s_cmp_ge_i32 s7, s88
	s_cselect_b64 s[46:47], -1, 0
	s_and_b64 vcc, exec, s[46:47]
	s_cbranch_vccnz .LBB0_61
	s_and_b32 s7, s7, 3
	s_lshl_b32 s14, s7, 13
	s_add_i32 s14, s16, s14
	s_mov_b32 m0, s14
	s_nop 0
	global_load_lds_dwordx4 v[212:213], off
	s_lshl_b32 s7, s7, 12
	s_add_i32 s7, s55, s7
	s_mov_b32 m0, s7
	s_nop 0
	global_load_lds_dwordx4 v[210:211], off
.LBB0_61:
	s_add_i32 s7, s57, 6
	s_cmp_ge_i32 s7, s88
	s_cbranch_scc1 .LBB0_63
	s_and_b32 s7, s91, 0x6000
	s_add_i32 s7, s56, s7
	s_mov_b32 m0, s7
	s_nop 0
	global_load_lds_dwordx4 v[208:209], off

; #define MFMA32(a, b, c) __builtin_amdgcn_mfma_f32_32x32x16_bf16((a), (b), (c), 0, 0, 0)
; __device__ __forceinline__ float max3f(float a, float b, float c) { float r; asm("v_max3_f32 %0, %1, %2, %3" : "=v"(r) : "v"(a), "v"(b), "v"(c)); return r; }
; __device__ __forceinline__ float xhalf_max(float v) { auto rr = __builtin_amdgcn_permlane32_swap(__float_as_uint(v), __float_as_uint(v), false, false); return __builtin_fmaxf(__uint_as_float(rr[0]), __uint_as_float(rr[1])); }
; #define PV_IDX(g) (((g) & 1) * 4 + PV_KS(g))
; template <int DQK, int DV, bool MLA>
; __device__ __forceinline__ void attn_pass(LAS unsigned char* lds, const bf16_t* Qrow, const bf16_t* K0, int pitchK, const bf16_t* KrB, const bf16_t* Vt0, int NT, int q0w,
;                                           f32x16 (&o)[DV / 32], float& l_out, int tid) {
;     ...
;             float mx;
;             asm volatile("s_nop 11" : "+v"(s0), "+v"(s1));
;             {
;                 float a = max3f(s0[0], s0[1], s1[0]), b = max3f(s0[2], s0[3], s1[1]); a = max3f(a, s1[2], s1[3]);
; #pragma unroll
;                 for (int r = 4; r < 16; r += 4) { a = max3f(a, s0[r], s0[r + 1]); b = max3f(b, s0[r + 2], s0[r + 3]); a = max3f(a, s1[r], s1[r + 1]); b = max3f(b, s1[r + 2], s1[r + 3]); }
;                 mx = xhalf_max(__builtin_fmaxf(a, b)) - (MLA ? 0.f : m);
;             }
;             if (t == 0 || __any(mx > THR)) {
;                 if (pend) {
; #pragma unroll
;                     for (int g = 0; g < NG; ++g) {
;                         o[PV_D(g)] = MFMA32(vf[PV_IDX(g)], pf[PV_KS(g)], o[PV_D(g)]);
;                         if (NDV == 4 && g < 8) vf[PV_IDX(g)] = VFRAG(vp, PV_D(g) + 2, PV_KS(g));
;                     }
.LBB0_76:
	s_or_b64 exec, exec, s[6:7]
	v_max3_f32 v214, v66, v67, v50
	v_max3_f32 v215, v68, v69, v51
	v_max3_f32 v214, v214, v52, v53
	v_max3_f32 v215, v215, v72, v73
	v_max3_f32 v214, v214, v70, v71
	v_max3_f32 v215, v215, v56, v57
	v_max3_f32 v214, v214, v54, v55
	v_max3_f32 v215, v215, v76, v77
	v_max3_f32 v214, v214, v74, v75
	v_max3_f32 v215, v215, v60, v61
	v_max3_f32 v214, v214, v58, v59
	v_max3_f32 v215, v215, v80, v81
	v_max3_f32 v214, v214, v78, v79
	v_max3_f32 v215, v215, v64, v65
	v_max3_f32 v214, v214, v62, v63
	v_max_f32_e32 v214, v214, v215
	v_mov_b32_e32 v215, v214
	s_nop 1
	v_permlane32_swap_b32_e32 v214, v215
	v_max_f32_e32 v214, v214, v215
	v_cmp_lt_f32_e32 vcc, s66, v214
	s_cbranch_vccz .LBB0_80
	s_and_saveexec_b64 s[6:7], s[48:49]
	s_cbranch_execz .LBB0_79
	s_waitcnt lgkmcnt(15)
	v_mfma_f32_32x32x16_bf16 v[18:33], v[178:181], v[158:161], v[18:33]
	s_waitcnt lgkmcnt(15)
	v_mfma_f32_32x32x16_bf16 v[2:17], v[170:173], v[158:161], v[2:17]
	s_waitcnt lgkmcnt(15)
	v_mfma_f32_32x32x16_bf16 v[18:33], v[186:189], v[162:165], v[18:33]
	s_waitcnt lgkmcnt(15)
	v_mfma_f32_32x32x16_bf16 v[2:17], v[174:177], v[162:165], v[2:17]
	s_waitcnt lgkmcnt(15)
	v_mfma_f32_32x32x16_bf16 v[18:33], v[194:197], v[166:169], v[18:33]
	s_waitcnt lgkmcnt(14)
	v_mfma_f32_32x32x16_bf16 v[2:17], v[182:185], v[166:169], v[2:17]
	s_waitcnt lgkmcnt(13)
	v_mfma_f32_32x32x16_bf16 v[18:33], v[198:201], v[154:157], v[18:33]
	s_waitcnt lgkmcnt(12)
	v_mfma_f32_32x32x16_bf16 v[2:17], v[190:193], v[154:157], v[2:17]

; __device__ __forceinline__ unsigned cvtpk(float lo, float hi) { const f32x2 v = {lo, hi}; const bf16x2_t b = __builtin_convertvector(v, bf16x2_t); return __builtin_bit_cast(unsigned, b); }
; #define MFMA32(a, b, c) __builtin_amdgcn_mfma_f32_32x32x16_bf16((a), (b), (c), 0, 0, 0)
; template <int DQK, int DV, bool MLA>
; __device__ __forceinline__ void attn_pass(LAS unsigned char* lds, const bf16_t* Qrow, const bf16_t* K0, int pitchK, const bf16_t* KrB, const bf16_t* Vt0, int NT, int q0w,
;                                           f32x16 (&o)[DV / 32], float& l_out, int tid) {
;     ...
;             float ps = 0.f;
;             u32x4 pw[4];
;             float ps1 = 0.f;
;             if (pend) {
; #pragma unroll
;                 for (int g = 0; g <= NG; ++g) {
;                     if (g < NG) {
;                         o[PV_D(g)] = MFMA32(vf[PV_IDX(g)], pf[PV_KS(g)], o[PV_D(g)]);
;                         if (NDV == 4 && g < 8) vf[PV_IDX(g)] = VFRAG(vp, PV_D(g) + 2, PV_KS(g));
; #pragma unroll
;                         for (int e = g * EPG; e < (g + 1) * EPG; ++e) { if (e < 16) s0[e] = __builtin_amdgcn_exp2f(MLA ? s0[e] : s0[e] - m); else s1[e - 16] = __builtin_amdgcn_exp2f(MLA ? s1[e - 16] : s1[e - 16] - m); }
;                     }
;                     if (g > 0) {
; #pragma unroll
;                         for (int e = (g - 1) * EPG; e < g * EPG; ++e) {
;                             const float v = e < 16 ? s0[e] : s1[e - 16];
;                             if (e & 1) ps1 += v; else ps += v;
;                             if (e & 1) { const int j = e >> 1; pw[j >> 2][j & 3] = e < 16 ? cvtpk(s0[e - 1], s0[e]) : cvtpk(s1[e - 17], s1[e - 16]); }
;                         }
;                     }
;                     __builtin_amdgcn_sched_barrier(0);
;                 }
;             } else {
;                 float m2 = MLA ? 0.f : m; asm volatile("" : "+v"(m2));
; #pragma unroll
;                 for (int e = 0; e < 32; ++e) {
;                     if (e < 16) { s0[e] = __builtin_amdgcn_exp2f(MLA ? s0[e] + m2 : s0[e] - m2); ps += s0[e]; } else { s1[e - 16] = __builtin_amdgcn_exp2f(MLA ? s1[e - 16] + m2 : s1[e - 16] - m2); ps += s1[e - 16]; }
;                     if (e & 1) { const int j = e >> 1; pw[j >> 2][j & 3] = e < 16 ? cvtpk(s0[e - 1], s0[e]) : cvtpk(s1[e - 17], s1[e - 16]); }
;                 }
;             }
;             l += ps + ps1;
.LBB0_82:
	s_or_saveexec_b64 s[6:7], s[6:7]
	v_mov_b32_e32 v215, 0
	s_xor_b64 exec, exec, s[6:7]
	s_cbranch_execz .LBB0_84
	s_waitcnt lgkmcnt(12)
	v_mfma_f32_32x32x16_bf16 v[18:33], v[178:181], v[158:161], v[18:33]
	v_exp_f32_e32 v66, v66
	v_exp_f32_e32 v67, v67
	v_exp_f32_e32 v68, v68
	v_exp_f32_e32 v69, v69
	v_mfma_f32_32x32x16_bf16 v[2:17], v[170:173], v[158:161], v[2:17]
	v_cvt_pk_bf16_f32 v158, v66, v67
	v_cvt_pk_bf16_f32 v159, v68, v69
	v_exp_f32_e32 v70, v70
	v_exp_f32_e32 v71, v71
	v_exp_f32_e32 v72, v72
	v_exp_f32_e32 v73, v73
	v_mfma_f32_32x32x16_bf16 v[18:33], v[186:189], v[162:165], v[18:33]
	v_cvt_pk_bf16_f32 v160, v70, v71
	v_cvt_pk_bf16_f32 v161, v72, v73
	v_exp_f32_e32 v74, v74
	v_exp_f32_e32 v75, v75
	v_exp_f32_e32 v76, v76
	v_exp_f32_e32 v77, v77
	v_mfma_f32_32x32x16_bf16 v[2:17], v[174:177], v[162:165], v[2:17]
	v_cvt_pk_bf16_f32 v162, v74, v75
	v_add_f32_e64 v66, v68, v66
	v_add_f32_e64 v67, v69, v67
	v_cvt_pk_bf16_f32 v163, v76, v77
	v_pk_add_f32 v[66:67], v[70:71], v[66:67]
	v_exp_f32_e32 v78, v78
	v_pk_add_f32 v[66:67], v[72:73], v[66:67]
	v_exp_f32_e32 v79, v79
	v_exp_f32_e32 v80, v80
	v_exp_f32_e32 v81, v81
	v_pk_add_f32 v[66:67], v[74:75], v[66:67]
	v_mfma_f32_32x32x16_bf16 v[18:33], v[194:197], v[166:169], v[18:33]
	v_cvt_pk_bf16_f32 v164, v78, v79
	v_cvt_pk_bf16_f32 v165, v80, v81
	v_exp_f32_e32 v50, v50
	v_exp_f32_e32 v51, v51
	v_exp_f32_e32 v52, v52
	v_exp_f32_e32 v53, v53
	v_mfma_f32_32x32x16_bf16 v[2:17], v[182:185], v[166:169], v[2:17]
	v_cvt_pk_bf16_f32 v166, v50, v51
	v_cvt_pk_bf16_f32 v167, v52, v53
	v_exp_f32_e32 v54, v54
	v_exp_f32_e32 v55, v55
	v_exp_f32_e32 v56, v56
	v_exp_f32_e32 v57, v57
	v_mfma_f32_32x32x16_bf16 v[18:33], v[198:201], v[154:157], v[18:33]
	v_cvt_pk_bf16_f32 v168, v54, v55
	v_cvt_pk_bf16_f32 v169, v56, v57
	v_exp_f32_e32 v58, v58
	v_exp_f32_e32 v59, v59
	v_exp_f32_e32 v60, v60
	v_exp_f32_e32 v61, v61
	v_mfma_f32_32x32x16_bf16 v[2:17], v[190:193], v[154:157], v[2:17]
	v_cvt_pk_bf16_f32 v154, v58, v59
	v_cvt_pk_bf16_f32 v155, v60, v61
	v_exp_f32_e32 v62, v62
	v_exp_f32_e32 v63, v63
	v_exp_f32_e32 v64, v64
	v_exp_f32_e32 v65, v65
	v_pk_add_f32 v[66:67], v[76:77], v[66:67]
	v_pk_add_f32 v[50:51], v[52:53], v[50:51]
	v_cvt_pk_bf16_f32 v156, v62, v63
	v_pk_add_f32 v[66:67], v[78:79], v[66:67]
	v_pk_add_f32 v[50:51], v[54:55], v[50:51]
	v_pk_add_f32 v[66:67], v[80:81], v[66:67]
	v_pk_add_f32 v[50:51], v[56:57], v[50:51]
	v_pk_add_f32 v[66:67], v[58:59], v[66:67]
	v_pk_add_f32 v[50:51], v[60:61], v[50:51]
	v_pk_add_f32 v[66:67], v[62:63], v[66:67]
	v_pk_add_f32 v[50:51], v[64:65], v[50:51]
	v_cvt_pk_bf16_f32 v157, v64, v65
	v_pk_add_f32 v[214:215], v[66:67], v[50:51]

; #define ATT_DMA_V(tt, vslot) do { \
;         _Pragma("unroll") for (int j = 0; j < NVC; ++j) glds16(vsrc[j] + (size_t)(tt) * (512 * 64), (unsigned)__builtin_amdgcn_readfirstlane(lds0 + VOFF + (vslot) * VB + (wid + 8 * j) * 1024)); } while (0)
; template <int DQK, int DV, bool MLA>
; __device__ __forceinline__ void attn_pass(LAS unsigned char* lds, const bf16_t* Qrow, const bf16_t* K0, int pitchK, const bf16_t* KrB, const bf16_t* Vt0, int NT, int q0w,
;                                           f32x16 (&o)[DV / 32], float& l_out, int tid) {
;     ...
;         if (t + 2 < NT) ATT_DMA_V(t + 2, (t + 2) & 3);
.LBB0_101:
	s_add_i32 s7, s94, -1
	s_cmp_ge_i32 s7, s88
	s_cbranch_scc1 .LBB0_103
	s_and_b32 s7, s96, 0xc000
	s_add_i32 s7, s91, s7
	s_mov_b32 m0, s7
	s_nop 0
	global_load_lds_dwordx4 v[198:199], off
	s_addk_i32 s7, 0x2000
	s_mov_b32 m0, s7
	s_nop 0
	global_load_lds_dwordx4 v[200:201], off

; #define MFMA32(a, b, c) __builtin_amdgcn_mfma_f32_32x32x16_bf16((a), (b), (c), 0, 0, 0)
; __device__ __forceinline__ float max3f(float a, float b, float c) { float r; asm("v_max3_f32 %0, %1, %2, %3" : "=v"(r) : "v"(a), "v"(b), "v"(c)); return r; }
; __device__ __forceinline__ float xhalf_max(float v) { auto rr = __builtin_amdgcn_permlane32_swap(__float_as_uint(v), __float_as_uint(v), false, false); return __builtin_fmaxf(__uint_as_float(rr[0]), __uint_as_float(rr[1])); }
; #define PV_IDX(g) (((g) & 1) * 4 + PV_KS(g))
; template <int DQK, int DV, bool MLA>
; __device__ __forceinline__ void attn_pass(LAS unsigned char* lds, const bf16_t* Qrow, const bf16_t* K0, int pitchK, const bf16_t* KrB, const bf16_t* Vt0, int NT, int q0w,
;                                           f32x16 (&o)[DV / 32], float& l_out, int tid) {
;     ...
;             float mx;
;             asm volatile("s_nop 11" : "+v"(s0), "+v"(s1));
;             {
;                 float a = max3f(s0[0], s0[1], s1[0]), b = max3f(s0[2], s0[3], s1[1]); a = max3f(a, s1[2], s1[3]);
; #pragma unroll
;                 for (int r = 4; r < 16; r += 4) { a = max3f(a, s0[r], s0[r + 1]); b = max3f(b, s0[r + 2], s0[r + 3]); a = max3f(a, s1[r], s1[r + 1]); b = max3f(b, s1[r + 2], s1[r + 3]); }
;                 mx = xhalf_max(__builtin_fmaxf(a, b)) - (MLA ? 0.f : m);
;             }
;             if (t == 0 || __any(mx > THR)) {
;                 if (pend) {
; #pragma unroll
;                     for (int g = 0; g < NG; ++g) {
;                         o[PV_D(g)] = MFMA32(vf[PV_IDX(g)], pf[PV_KS(g)], o[PV_D(g)]);
;                         if (NDV == 4 && g < 8) vf[PV_IDX(g)] = VFRAG(vp, PV_D(g) + 2, PV_KS(g));
;                     }
;                     pend = false;
;                 }
;                 const float dl = t == 0 ? mx : fmaxf(mx, 0.f);
;                 m += dl;
;                 if constexpr (MLA) {
; #pragma unroll
;                     for (int r = 0; r < 16; ++r) { s0[r] -= dl; s1[r] -= dl; negm[r] = -m; }
;                 }
;                 const float a = __builtin_amdgcn_exp2f(-dl);
;                 l *= a;
; #pragma unroll
;                 for (int d = 0; d < NDV; ++d)
; #pragma unroll
;                     for (int r = 0; r < 16; ++r) o[d][r] *= a;
;             }
.LBB0_116:
	s_or_b64 exec, exec, s[6:7]
	v_max3_f32 v206, v98, v99, v82
	v_max3_f32 v207, v100, v101, v83
	v_max3_f32 v206, v206, v84, v85
	v_max3_f32 v207, v207, v104, v105
	v_max3_f32 v206, v206, v102, v103
	v_max3_f32 v207, v207, v88, v89
	v_max3_f32 v206, v206, v86, v87
	v_max3_f32 v207, v207, v108, v109
	v_max3_f32 v206, v206, v106, v107
	v_max3_f32 v207, v207, v92, v93
	v_max3_f32 v206, v206, v90, v91
	v_max3_f32 v207, v207, v112, v113
	v_max3_f32 v206, v206, v110, v111
	v_max3_f32 v207, v207, v96, v97
	v_max3_f32 v206, v206, v94, v95
	v_max_f32_e32 v206, v206, v207
	v_mov_b32_e32 v207, v206
	s_nop 1
	v_permlane32_swap_b32_e32 v206, v207
	v_max_f32_e32 v206, v206, v207
	v_sub_f32_e32 v206, v206, v244
	v_cmp_lt_f32_e32 vcc, s66, v206
	s_cbranch_vccz .LBB0_120
	s_and_saveexec_b64 s[6:7], s[54:55]
	s_cbranch_execz .LBB0_119
	s_waitcnt lgkmcnt(7)
	v_mfma_f32_32x32x16_bf16 v[66:81], v[170:173], v[34:37], v[66:81]
	s_waitcnt lgkmcnt(6)
	v_mfma_f32_32x32x16_bf16 v[50:65], v[162:165], v[34:37], v[50:65]
	ds_read_b128 v[170:173], v246 offset:40960
	ds_read_b128 v[162:165], v246 offset:45056
	s_waitcnt lgkmcnt(1)
	v_mfma_f32_32x32x16_bf16 v[18:33], v[170:173], v[34:37], v[18:33]
	s_waitcnt lgkmcnt(0)
	v_mfma_f32_32x32x16_bf16 v[2:17], v[162:165], v[34:37], v[2:17]
	v_mfma_f32_32x32x16_bf16 v[66:81], v[178:181], v[38:41], v[66:81]
	v_mfma_f32_32x32x16_bf16 v[50:65], v[166:169], v[38:41], v[50:65]
	ds_read_b128 v[178:181], v245 offset:40960
	ds_read_b128 v[166:169], v245 offset:45056
	s_waitcnt lgkmcnt(1)
	v_mfma_f32_32x32x16_bf16 v[18:33], v[178:181], v[38:41], v[18:33]
	s_waitcnt lgkmcnt(0)
	v_mfma_f32_32x32x16_bf16 v[2:17], v[166:169], v[38:41], v[2:17]
	v_mfma_f32_32x32x16_bf16 v[66:81], v[186:189], v[42:45], v[66:81]
	v_mfma_f32_32x32x16_bf16 v[50:65], v[174:177], v[42:45], v[50:65]
	ds_read_b128 v[186:189], v222 offset:40960
	ds_read_b128 v[174:177], v222 offset:45056
	s_waitcnt lgkmcnt(1)
	v_mfma_f32_32x32x16_bf16 v[18:33], v[186:189], v[42:45], v[18:33]
	s_waitcnt lgkmcnt(0)
	v_mfma_f32_32x32x16_bf16 v[2:17], v[174:177], v[42:45], v[2:17]
	v_mfma_f32_32x32x16_bf16 v[66:81], v[190:193], v[46:49], v[66:81]
	v_mfma_f32_32x32x16_bf16 v[50:65], v[182:185], v[46:49], v[50:65]
	ds_read_b128 v[190:193], v221 offset:40960
	ds_read_b128 v[182:185], v221 offset:45056
	s_waitcnt lgkmcnt(1)
	v_mfma_f32_32x32x16_bf16 v[18:33], v[190:193], v[46:49], v[18:33]
	s_waitcnt lgkmcnt(0)
	v_mfma_f32_32x32x16_bf16 v[2:17], v[182:185], v[46:49], v[2:17]

; #define ATT_DMA_V(tt, vslot) do { \
;         _Pragma("unroll") for (int j = 0; j < NVC; ++j) glds16(vsrc[j] + (size_t)(tt) * (512 * 64), (unsigned)__builtin_amdgcn_readfirstlane(lds0 + VOFF + (vslot) * VB + (wid + 8 * j) * 1024)); } while (0)
; template <int DQK, int DV, bool MLA>
; __device__ __forceinline__ void attn_pass(LAS unsigned char* lds, const bf16_t* Qrow, const bf16_t* K0, int pitchK, const bf16_t* KrB, const bf16_t* Vt0, int NT, int q0w,
;                                           f32x16 (&o)[DV / 32], float& l_out, int tid) {
;     ...
;         if (t + 2 < NT) ATT_DMA_V(t + 2, (t + 2) & 3);
.LBB0_138:
	s_add_i32 s7, s55, -1
	s_cmp_ge_i32 s7, s88
	s_cbranch_scc1 .LBB0_140
	s_and_b32 s7, s57, 0xc000
	s_add_i32 s7, s52, s7
	s_mov_b32 m0, s7
	s_nop 0
	global_load_lds_dwordx4 v[196:197], off
	s_addk_i32 s7, 0x2000
	s_mov_b32 m0, s7
	s_nop 0
	global_load_lds_dwordx4 v[198:199], off

; #define MFMA32(a, b, c) __builtin_amdgcn_mfma_f32_32x32x16_bf16((a), (b), (c), 0, 0, 0)
; __device__ __forceinline__ float max3f(float a, float b, float c) { float r; asm("v_max3_f32 %0, %1, %2, %3" : "=v"(r) : "v"(a), "v"(b), "v"(c)); return r; }
; __device__ __forceinline__ float xhalf_max(float v) { auto rr = __builtin_amdgcn_permlane32_swap(__float_as_uint(v), __float_as_uint(v), false, false); return __builtin_fmaxf(__uint_as_float(rr[0]), __uint_as_float(rr[1])); }
; #define PV_IDX(g) (((g) & 1) * 4 + PV_KS(g))
; template <int DQK, int DV, bool MLA>
; __device__ __forceinline__ void attn_pass(LAS unsigned char* lds, const bf16_t* Qrow, const bf16_t* K0, int pitchK, const bf16_t* KrB, const bf16_t* Vt0, int NT, int q0w,
;                                           f32x16 (&o)[DV / 32], float& l_out, int tid) {
;     ...
;             float mx;
;             asm volatile("s_nop 11" : "+v"(s0), "+v"(s1));
;             {
;                 float a = max3f(s0[0], s0[1], s1[0]), b = max3f(s0[2], s0[3], s1[1]); a = max3f(a, s1[2], s1[3]);
; #pragma unroll
;                 for (int r = 4; r < 16; r += 4) { a = max3f(a, s0[r], s0[r + 1]); b = max3f(b, s0[r + 2], s0[r + 3]); a = max3f(a, s1[r], s1[r + 1]); b = max3f(b, s1[r + 2], s1[r + 3]); }
;                 mx = xhalf_max(__builtin_fmaxf(a, b)) - (MLA ? 0.f : m);
;             }
;             if (t == 0 || __any(mx > THR)) {
;                 if (pend) {
; #pragma unroll
;                     for (int g = 0; g < NG; ++g) {
;                         o[PV_D(g)] = MFMA32(vf[PV_IDX(g)], pf[PV_KS(g)], o[PV_D(g)]);
;                         if (NDV == 4 && g < 8) vf[PV_IDX(g)] = VFRAG(vp, PV_D(g) + 2, PV_KS(g));
;                     }
;                     pend = false;
;                 }
;                 const float dl = t == 0 ? mx : fmaxf(mx, 0.f);
;                 m += dl;
;                 if constexpr (MLA) {
; #pragma unroll
;                     for (int r = 0; r < 16; ++r) { s0[r] -= dl; s1[r] -= dl; negm[r] = -m; }
;                 }
;                 const float a = __builtin_amdgcn_exp2f(-dl);
;                 l *= a;
; #pragma unroll
;                 for (int d = 0; d < NDV; ++d)
; #pragma unroll
;                     for (int r = 0; r < 16; ++r) o[d][r] *= a;
;             }
.LBB0_153:
	s_or_b64 exec, exec, s[6:7]
	v_max3_f32 v204, v98, v99, v82
	v_max3_f32 v205, v100, v101, v83
	v_max3_f32 v204, v204, v84, v85
	v_max3_f32 v205, v205, v104, v105
	v_max3_f32 v204, v204, v102, v103
	v_max3_f32 v205, v205, v88, v89
	v_max3_f32 v204, v204, v86, v87
	v_max3_f32 v205, v205, v108, v109
	v_max3_f32 v204, v204, v106, v107
	v_max3_f32 v205, v205, v92, v93
	v_max3_f32 v204, v204, v90, v91
	v_max3_f32 v205, v205, v112, v113
	v_max3_f32 v204, v204, v110, v111
	v_max3_f32 v205, v205, v96, v97
	v_max3_f32 v204, v204, v94, v95
	v_max_f32_e32 v204, v204, v205
	v_mov_b32_e32 v205, v204
	s_nop 1
	v_permlane32_swap_b32_e32 v204, v205
	v_max_f32_e32 v204, v204, v205
	v_sub_f32_e32 v204, v204, v207
	v_cmp_lt_f32_e32 vcc, s66, v204
	s_cbranch_vccz .LBB0_157
	s_and_saveexec_b64 s[6:7], s[48:49]
	s_cbranch_execz .LBB0_156
	s_waitcnt lgkmcnt(7)
	v_mfma_f32_32x32x16_bf16 v[66:81], v[170:173], v[50:53], v[66:81]
	s_waitcnt lgkmcnt(6)
	v_mfma_f32_32x32x16_bf16 v[34:49], v[162:165], v[50:53], v[34:49]
	ds_read_b128 v[170:173], v221 offset:40960
	ds_read_b128 v[162:165], v221 offset:45056
	s_waitcnt lgkmcnt(1)
	v_mfma_f32_32x32x16_bf16 v[18:33], v[170:173], v[50:53], v[18:33]
	s_waitcnt lgkmcnt(0)
	v_mfma_f32_32x32x16_bf16 v[2:17], v[162:165], v[50:53], v[2:17]
	v_mfma_f32_32x32x16_bf16 v[66:81], v[178:181], v[54:57], v[66:81]
	v_mfma_f32_32x32x16_bf16 v[34:49], v[166:169], v[54:57], v[34:49]
	ds_read_b128 v[178:181], v215 offset:40960
	ds_read_b128 v[166:169], v215 offset:45056
	s_waitcnt lgkmcnt(1)
	v_mfma_f32_32x32x16_bf16 v[18:33], v[178:181], v[54:57], v[18:33]
	s_waitcnt lgkmcnt(0)
	v_mfma_f32_32x32x16_bf16 v[2:17], v[166:169], v[54:57], v[2:17]
	v_mfma_f32_32x32x16_bf16 v[66:81], v[186:189], v[58:61], v[66:81]
	v_mfma_f32_32x32x16_bf16 v[34:49], v[174:177], v[58:61], v[34:49]
	ds_read_b128 v[186:189], v214 offset:40960
	ds_read_b128 v[174:177], v214 offset:45056
	s_waitcnt lgkmcnt(1)
	v_mfma_f32_32x32x16_bf16 v[18:33], v[186:189], v[58:61], v[18:33]
	s_waitcnt lgkmcnt(0)
	v_mfma_f32_32x32x16_bf16 v[2:17], v[174:177], v[58:61], v[2:17]
	v_mfma_f32_32x32x16_bf16 v[66:81], v[190:193], v[62:65], v[66:81]
	v_mfma_f32_32x32x16_bf16 v[34:49], v[182:185], v[62:65], v[34:49]
	ds_read_b128 v[190:193], v213 offset:40960
	ds_read_b128 v[182:185], v213 offset:45056
	s_waitcnt lgkmcnt(1)
	v_mfma_f32_32x32x16_bf16 v[18:33], v[190:193], v[62:65], v[18:33]
	s_waitcnt lgkmcnt(0)
	v_mfma_f32_32x32x16_bf16 v[2:17], v[182:185], v[62:65], v[2:17]
